# gate/up GEMM: per-block s_setprio flips removed, one static s_setprio 1 for the trailing half-workgroup during the phase
# speedup vs baseline: 1.0030x; 1.0030x over previous
.LBB0_877:
	s_cmp_lg_u32 s7, 1
	s_cbranch_scc1 .Lp4_prio_done
	s_setprio 1

.LBB0_882:
	s_ashr_i32 s9, s8, 31
	s_lshl_b64 s[76:77], s[8:9], 19
	s_add_u32 s76, s57, s76
	s_addc_u32 s77, s58, s77
	s_and_b64 s[78:79], s[12:13], exec
	s_cselect_b32 s9, s77, s81
	s_cselect_b32 s92, s76, s80
	s_ashr_i32 s75, s74, 31
	s_lshl_b64 s[78:79], s[74:75], 19
	s_add_u32 s78, s46, s78
	s_addc_u32 s79, s56, s79
	s_and_b64 s[12:13], s[12:13], exec
	s_cselect_b32 s12, s79, s83
	s_cselect_b32 s13, s78, s82
	s_add_u32 s80, s80, 0x40080
	s_addc_u32 s81, s81, 0
	s_add_u32 s75, s82, 0x100
	s_addc_u32 s93, s83, 0
	s_mov_b32 s94, -2
	v_add_u32_e32 v140, s63, v143
	ds_read_b128 v[146:149], v140
	ds_read_b128 v[150:153], v140 offset:1024
	ds_read_b128 v[154:157], v140 offset:2048
	ds_read_b128 v[158:161], v140 offset:3072
	v_add_u32_e32 v140, s10, v143
	ds_read_b128 v[162:165], v140
	ds_read_b128 v[166:169], v140 offset:1024
	ds_read_b128 v[170:173], v140 offset:2048
	ds_read_b128 v[174:177], v140 offset:3072
	s_add_u32 s55, s80, 0xfffc0080
	s_addc_u32 s82, s81, -1
	s_cmp_eq_u32 s94, 12
	s_cselect_b32 s85, s9, s82
	s_cselect_b32 s84, s92, s55
	s_cselect_b32 s83, s12, s93
	s_cselect_b32 s82, s13, s75
	v_lshl_add_u64 v[140:141], s[80:81], 0, v[136:137]
	s_add_i32 m0, s60, 0xc000
	ds_read_b128 v[178:181], v145
	ds_read_b128 v[182:185], v145 offset:1024
	ds_read_b128 v[186:189], v145 offset:2048
	ds_read_b128 v[192:195], v145 offset:3072
	ds_read_b128 v[196:199], v145 offset:4096
	ds_read_b128 v[200:203], v145 offset:5120
	ds_read_b128 v[204:207], v145 offset:6144
	ds_read_b128 v[208:211], v145 offset:7168
	global_load_lds_dwordx4 v[140:141], off
	v_lshl_add_u64 v[140:141], s[80:81], 0, v[138:139]
	s_add_i32 m0, s60, 0xe000
	s_nop 0
	global_load_lds_dwordx4 v[140:141], off
	s_waitcnt vmcnt(8)
	s_waitcnt lgkmcnt(0)
	s_barrier
	s_waitcnt lgkmcnt(0)
	v_mfma_f32_16x16x32_bf16 v[126:129], v[146:149], v[178:181], 0
	v_mfma_f32_16x16x32_bf16 v[122:125], v[154:157], v[178:181], 0
	v_mfma_f32_16x16x32_bf16 v[110:113], v[146:149], v[186:189], 0
	v_mfma_f32_16x16x32_bf16 v[106:109], v[154:157], v[186:189], 0
	v_mfma_f32_16x16x32_bf16 v[94:97], v[146:149], v[196:199], 0
	v_mfma_f32_16x16x32_bf16 v[90:93], v[154:157], v[196:199], 0
	v_mfma_f32_16x16x32_bf16 v[78:81], v[146:149], v[204:207], 0
	v_mfma_f32_16x16x32_bf16 v[74:77], v[154:157], v[204:207], 0
	v_mfma_f32_16x16x32_bf16 v[126:129], v[150:153], v[182:185], v[126:129]
	v_mfma_f32_16x16x32_bf16 v[122:125], v[158:161], v[182:185], v[122:125]
	v_mfma_f32_16x16x32_bf16 v[110:113], v[150:153], v[192:195], v[110:113]
	v_mfma_f32_16x16x32_bf16 v[106:109], v[158:161], v[192:195], v[106:109]
	v_mfma_f32_16x16x32_bf16 v[94:97], v[150:153], v[200:203], v[94:97]
	v_mfma_f32_16x16x32_bf16 v[90:93], v[158:161], v[200:203], v[90:93]
	v_mfma_f32_16x16x32_bf16 v[78:81], v[150:153], v[208:211], v[78:81]
	v_mfma_f32_16x16x32_bf16 v[74:77], v[158:161], v[208:211], v[74:77]
	v_mfma_f32_16x16x32_bf16 v[118:121], v[162:165], v[178:181], 0
	v_mfma_f32_16x16x32_bf16 v[114:117], v[170:173], v[178:181], 0
	v_mfma_f32_16x16x32_bf16 v[102:105], v[162:165], v[186:189], 0
	v_mfma_f32_16x16x32_bf16 v[98:101], v[170:173], v[186:189], 0
	v_mfma_f32_16x16x32_bf16 v[86:89], v[162:165], v[196:199], 0
	v_mfma_f32_16x16x32_bf16 v[82:85], v[170:173], v[196:199], 0
	v_mfma_f32_16x16x32_bf16 v[70:73], v[162:165], v[204:207], 0
	v_mfma_f32_16x16x32_bf16 v[66:69], v[170:173], v[204:207], 0
	v_mfma_f32_16x16x32_bf16 v[118:121], v[166:169], v[182:185], v[118:121]
	v_mfma_f32_16x16x32_bf16 v[114:117], v[174:177], v[182:185], v[114:117]
	v_mfma_f32_16x16x32_bf16 v[102:105], v[166:169], v[192:195], v[102:105]
	v_mfma_f32_16x16x32_bf16 v[98:101], v[174:177], v[192:195], v[98:101]
	v_mfma_f32_16x16x32_bf16 v[86:89], v[166:169], v[200:203], v[86:89]
	v_mfma_f32_16x16x32_bf16 v[82:85], v[174:177], v[200:203], v[82:85]
	v_mfma_f32_16x16x32_bf16 v[70:73], v[166:169], v[208:211], v[70:73]
	v_mfma_f32_16x16x32_bf16 v[66:69], v[174:177], v[208:211], v[66:69]
	s_barrier
	s_add_i32 s55, s63, s59
	v_lshl_add_u64 v[140:141], s[82:83], 0, v[0:1]
	s_mov_b32 m0, s55
	ds_read_b128 v[178:181], v145 offset:16384
	ds_read_b128 v[182:185], v145 offset:17408
	ds_read_b128 v[186:189], v145 offset:18432
	ds_read_b128 v[192:195], v145 offset:19456
	ds_read_b128 v[196:199], v145 offset:20480
	ds_read_b128 v[200:203], v145 offset:21504
	ds_read_b128 v[204:207], v145 offset:22528
	ds_read_b128 v[208:211], v145 offset:23552
	global_load_lds_dwordx4 v[140:141], off
	s_add_i32 m0, s55, 0x2000
	s_add_u32 s96, s82, 0x40000
	v_lshl_add_u64 v[212:213], s[82:83], 0, v[134:135]
	s_addc_u32 s97, s83, 0
	s_add_i32 s55, s10, s59
	global_load_lds_dwordx4 v[212:213], off
	v_lshl_add_u64 v[214:215], s[96:97], 0, v[0:1]
	s_mov_b32 m0, s55
	v_lshl_add_u64 v[216:217], s[84:85], 0, v[132:133]
	global_load_lds_dwordx4 v[214:215], off
	v_lshl_add_u64 v[214:215], s[96:97], 0, v[134:135]
	s_add_i32 m0, s55, 0x2000
	s_nop 0
	global_load_lds_dwordx4 v[214:215], off
	v_lshl_add_u64 v[214:215], s[84:85], 0, v[130:131]
	s_mov_b32 m0, s60
	s_nop 0
	global_load_lds_dwordx4 v[214:215], off
	s_mov_b32 m0, s61
	s_nop 0
	global_load_lds_dwordx4 v[216:217], off
	s_waitcnt vmcnt(8)
	s_waitcnt lgkmcnt(0)
	s_barrier
	s_waitcnt lgkmcnt(0)
	v_mfma_f32_16x16x32_bf16 v[62:65], v[146:149], v[178:181], 0
	v_mfma_f32_16x16x32_bf16 v[58:61], v[154:157], v[178:181], 0
	v_mfma_f32_16x16x32_bf16 v[46:49], v[146:149], v[186:189], 0
	v_mfma_f32_16x16x32_bf16 v[42:45], v[154:157], v[186:189], 0
	v_mfma_f32_16x16x32_bf16 v[30:33], v[146:149], v[196:199], 0
	v_mfma_f32_16x16x32_bf16 v[26:29], v[154:157], v[196:199], 0
	v_mfma_f32_16x16x32_bf16 v[14:17], v[146:149], v[204:207], 0
	v_mfma_f32_16x16x32_bf16 v[10:13], v[154:157], v[204:207], 0
	v_mfma_f32_16x16x32_bf16 v[62:65], v[150:153], v[182:185], v[62:65]
	v_mfma_f32_16x16x32_bf16 v[58:61], v[158:161], v[182:185], v[58:61]
	v_mfma_f32_16x16x32_bf16 v[46:49], v[150:153], v[192:195], v[46:49]
	v_mfma_f32_16x16x32_bf16 v[42:45], v[158:161], v[192:195], v[42:45]
	v_mfma_f32_16x16x32_bf16 v[30:33], v[150:153], v[200:203], v[30:33]
	v_mfma_f32_16x16x32_bf16 v[26:29], v[158:161], v[200:203], v[26:29]
	v_mfma_f32_16x16x32_bf16 v[14:17], v[150:153], v[208:211], v[14:17]
	v_mfma_f32_16x16x32_bf16 v[10:13], v[158:161], v[208:211], v[10:13]
	v_mfma_f32_16x16x32_bf16 v[54:57], v[162:165], v[178:181], 0
	v_mfma_f32_16x16x32_bf16 v[50:53], v[170:173], v[178:181], 0
	v_mfma_f32_16x16x32_bf16 v[38:41], v[162:165], v[186:189], 0
	v_mfma_f32_16x16x32_bf16 v[34:37], v[170:173], v[186:189], 0
	v_mfma_f32_16x16x32_bf16 v[22:25], v[162:165], v[196:199], 0
	v_mfma_f32_16x16x32_bf16 v[18:21], v[170:173], v[196:199], 0
	v_mfma_f32_16x16x32_bf16 v[6:9], v[162:165], v[204:207], 0
	v_mfma_f32_16x16x32_bf16 v[2:5], v[170:173], v[204:207], 0
	v_mfma_f32_16x16x32_bf16 v[54:57], v[166:169], v[182:185], v[54:57]
	v_mfma_f32_16x16x32_bf16 v[50:53], v[174:177], v[182:185], v[50:53]
	v_mfma_f32_16x16x32_bf16 v[38:41], v[166:169], v[192:195], v[38:41]
	v_mfma_f32_16x16x32_bf16 v[34:37], v[174:177], v[192:195], v[34:37]
	v_mfma_f32_16x16x32_bf16 v[22:25], v[166:169], v[200:203], v[22:25]
	v_mfma_f32_16x16x32_bf16 v[18:21], v[174:177], v[200:203], v[18:21]
	v_mfma_f32_16x16x32_bf16 v[6:9], v[166:169], v[208:211], v[6:9]
	v_mfma_f32_16x16x32_bf16 v[2:5], v[174:177], v[208:211], v[2:5]
	s_barrier
	v_add_u32_e32 v158, s11, v143
	v_add_u32_e32 v174, s67, v143
	ds_read_b128 v[146:149], v158
	ds_read_b128 v[150:153], v158 offset:1024
	ds_read_b128 v[154:157], v158 offset:2048
	ds_read_b128 v[158:161], v158 offset:3072
	ds_read_b128 v[162:165], v174
	ds_read_b128 v[166:169], v174 offset:1024
	ds_read_b128 v[170:173], v174 offset:2048
	ds_read_b128 v[174:177], v174 offset:3072
	s_add_u32 s84, s84, 0x40000
	s_addc_u32 s85, s85, 0
	s_mov_b32 m0, s68
	v_lshl_add_u64 v[218:219], s[84:85], 0, v[130:131]
	ds_read_b128 v[178:181], v145 offset:32768
	ds_read_b128 v[182:185], v145 offset:33792
	ds_read_b128 v[186:189], v145 offset:34816
	ds_read_b128 v[192:195], v145 offset:35840
	ds_read_b128 v[196:199], v145 offset:36864
	ds_read_b128 v[200:203], v145 offset:37888
	ds_read_b128 v[204:207], v145 offset:38912
	ds_read_b128 v[208:211], v145 offset:39936
	global_load_lds_dwordx4 v[218:219], off
	v_lshl_add_u64 v[218:219], s[84:85], 0, v[132:133]
	s_mov_b32 m0, s69
	s_nop 0
	global_load_lds_dwordx4 v[218:219], off
	s_waitcnt vmcnt(8)
	s_waitcnt lgkmcnt(0)
	s_barrier
	s_waitcnt lgkmcnt(0)
	v_mfma_f32_16x16x32_bf16 v[126:129], v[146:149], v[178:181], v[126:129]
	v_mfma_f32_16x16x32_bf16 v[122:125], v[154:157], v[178:181], v[122:125]
	v_mfma_f32_16x16x32_bf16 v[110:113], v[146:149], v[186:189], v[110:113]
	v_mfma_f32_16x16x32_bf16 v[106:109], v[154:157], v[186:189], v[106:109]
	v_mfma_f32_16x16x32_bf16 v[94:97], v[146:149], v[196:199], v[94:97]
	v_mfma_f32_16x16x32_bf16 v[90:93], v[154:157], v[196:199], v[90:93]
	v_mfma_f32_16x16x32_bf16 v[78:81], v[146:149], v[204:207], v[78:81]
	v_mfma_f32_16x16x32_bf16 v[74:77], v[154:157], v[204:207], v[74:77]
	v_mfma_f32_16x16x32_bf16 v[126:129], v[150:153], v[182:185], v[126:129]
	v_mfma_f32_16x16x32_bf16 v[122:125], v[158:161], v[182:185], v[122:125]
	v_mfma_f32_16x16x32_bf16 v[110:113], v[150:153], v[192:195], v[110:113]
	v_mfma_f32_16x16x32_bf16 v[106:109], v[158:161], v[192:195], v[106:109]
	v_mfma_f32_16x16x32_bf16 v[94:97], v[150:153], v[200:203], v[94:97]
	v_mfma_f32_16x16x32_bf16 v[90:93], v[158:161], v[200:203], v[90:93]
	v_mfma_f32_16x16x32_bf16 v[78:81], v[150:153], v[208:211], v[78:81]
	v_mfma_f32_16x16x32_bf16 v[74:77], v[158:161], v[208:211], v[74:77]
	v_mfma_f32_16x16x32_bf16 v[118:121], v[162:165], v[178:181], v[118:121]
	v_mfma_f32_16x16x32_bf16 v[114:117], v[170:173], v[178:181], v[114:117]
	v_mfma_f32_16x16x32_bf16 v[102:105], v[162:165], v[186:189], v[102:105]
	v_mfma_f32_16x16x32_bf16 v[98:101], v[170:173], v[186:189], v[98:101]
	v_mfma_f32_16x16x32_bf16 v[86:89], v[162:165], v[196:199], v[86:89]
	v_mfma_f32_16x16x32_bf16 v[82:85], v[170:173], v[196:199], v[82:85]
	v_mfma_f32_16x16x32_bf16 v[70:73], v[162:165], v[204:207], v[70:73]
	v_mfma_f32_16x16x32_bf16 v[66:69], v[170:173], v[204:207], v[66:69]
	v_mfma_f32_16x16x32_bf16 v[118:121], v[166:169], v[182:185], v[118:121]
	v_mfma_f32_16x16x32_bf16 v[114:117], v[174:177], v[182:185], v[114:117]
	v_mfma_f32_16x16x32_bf16 v[102:105], v[166:169], v[192:195], v[102:105]
	v_mfma_f32_16x16x32_bf16 v[98:101], v[174:177], v[192:195], v[98:101]
	v_mfma_f32_16x16x32_bf16 v[86:89], v[166:169], v[200:203], v[86:89]
	v_mfma_f32_16x16x32_bf16 v[82:85], v[174:177], v[200:203], v[82:85]
	v_mfma_f32_16x16x32_bf16 v[70:73], v[166:169], v[208:211], v[70:73]
	v_mfma_f32_16x16x32_bf16 v[66:69], v[174:177], v[208:211], v[66:69]
	s_barrier
	s_add_i32 s55, s11, s59
	v_lshl_add_u64 v[140:141], v[140:141], 0, s[50:51]
	s_mov_b32 m0, s55
	ds_read_b128 v[178:181], v145 offset:49152
	ds_read_b128 v[182:185], v145 offset:50176
	ds_read_b128 v[186:189], v145 offset:51200
	ds_read_b128 v[192:195], v145 offset:52224
	ds_read_b128 v[196:199], v145 offset:53248
	ds_read_b128 v[200:203], v145 offset:54272
	ds_read_b128 v[204:207], v145 offset:55296
	ds_read_b128 v[208:211], v145 offset:56320
	global_load_lds_dwordx4 v[140:141], off
	s_add_i32 m0, s55, 0x2000
	s_add_u32 s82, s82, 0x40080
	v_lshl_add_u64 v[140:141], v[212:213], 0, s[50:51]
	s_addc_u32 s83, s83, 0
	s_add_i32 s55, s67, s59
	global_load_lds_dwordx4 v[140:141], off
	v_lshl_add_u64 v[140:141], s[82:83], 0, v[0:1]
	s_mov_b32 m0, s55
	s_nop 0
	global_load_lds_dwordx4 v[140:141], off
	v_lshl_add_u64 v[140:141], s[82:83], 0, v[134:135]
	s_add_i32 m0, s55, 0x2000
	s_nop 0
	global_load_lds_dwordx4 v[140:141], off
	v_lshl_add_u64 v[140:141], v[214:215], 0, s[50:51]
	s_mov_b32 m0, s86
	s_nop 0
	global_load_lds_dwordx4 v[140:141], off
	v_lshl_add_u64 v[140:141], v[216:217], 0, s[50:51]
	s_mov_b32 m0, s87
	s_nop 0
	global_load_lds_dwordx4 v[140:141], off
	s_waitcnt vmcnt(8)
	s_waitcnt lgkmcnt(0)
	s_barrier
	s_waitcnt lgkmcnt(0)
	v_mfma_f32_16x16x32_bf16 v[62:65], v[146:149], v[178:181], v[62:65]
	v_mfma_f32_16x16x32_bf16 v[58:61], v[154:157], v[178:181], v[58:61]
	v_mfma_f32_16x16x32_bf16 v[46:49], v[146:149], v[186:189], v[46:49]
	v_mfma_f32_16x16x32_bf16 v[42:45], v[154:157], v[186:189], v[42:45]
	v_mfma_f32_16x16x32_bf16 v[30:33], v[146:149], v[196:199], v[30:33]
	v_mfma_f32_16x16x32_bf16 v[26:29], v[154:157], v[196:199], v[26:29]
	v_mfma_f32_16x16x32_bf16 v[14:17], v[146:149], v[204:207], v[14:17]
	v_mfma_f32_16x16x32_bf16 v[10:13], v[154:157], v[204:207], v[10:13]
	v_mfma_f32_16x16x32_bf16 v[62:65], v[150:153], v[182:185], v[62:65]
	v_mfma_f32_16x16x32_bf16 v[58:61], v[158:161], v[182:185], v[58:61]
	v_mfma_f32_16x16x32_bf16 v[46:49], v[150:153], v[192:195], v[46:49]
	v_mfma_f32_16x16x32_bf16 v[42:45], v[158:161], v[192:195], v[42:45]
	v_mfma_f32_16x16x32_bf16 v[30:33], v[150:153], v[200:203], v[30:33]
	v_mfma_f32_16x16x32_bf16 v[26:29], v[158:161], v[200:203], v[26:29]
	v_mfma_f32_16x16x32_bf16 v[14:17], v[150:153], v[208:211], v[14:17]
	v_mfma_f32_16x16x32_bf16 v[10:13], v[158:161], v[208:211], v[10:13]
	v_mfma_f32_16x16x32_bf16 v[54:57], v[162:165], v[178:181], v[54:57]
	v_mfma_f32_16x16x32_bf16 v[50:53], v[170:173], v[178:181], v[50:53]
	v_mfma_f32_16x16x32_bf16 v[38:41], v[162:165], v[186:189], v[38:41]
	v_mfma_f32_16x16x32_bf16 v[34:37], v[170:173], v[186:189], v[34:37]
	v_mfma_f32_16x16x32_bf16 v[22:25], v[162:165], v[196:199], v[22:25]
	v_mfma_f32_16x16x32_bf16 v[18:21], v[170:173], v[196:199], v[18:21]
	v_mfma_f32_16x16x32_bf16 v[6:9], v[162:165], v[204:207], v[6:9]
	v_mfma_f32_16x16x32_bf16 v[2:5], v[170:173], v[204:207], v[2:5]
	v_mfma_f32_16x16x32_bf16 v[54:57], v[166:169], v[182:185], v[54:57]
	v_mfma_f32_16x16x32_bf16 v[50:53], v[174:177], v[182:185], v[50:53]
	v_mfma_f32_16x16x32_bf16 v[38:41], v[166:169], v[192:195], v[38:41]
	v_mfma_f32_16x16x32_bf16 v[34:37], v[174:177], v[192:195], v[34:37]
	v_mfma_f32_16x16x32_bf16 v[22:25], v[166:169], v[200:203], v[22:25]
	v_mfma_f32_16x16x32_bf16 v[18:21], v[174:177], v[200:203], v[18:21]
	v_mfma_f32_16x16x32_bf16 v[6:9], v[166:169], v[208:211], v[6:9]
	v_mfma_f32_16x16x32_bf16 v[2:5], v[174:177], v[208:211], v[2:5]
	s_barrier
	s_add_i32 s94, s94, 2
	s_add_u32 s80, s80, 0x100
	s_addc_u32 s81, s81, 0
	s_add_u32 s75, s75, 0x100
	s_addc_u32 s93, s93, 0
.LBB0_883:
	v_add_u32_e32 v140, s63, v143
	ds_read_b128 v[146:149], v140
	ds_read_b128 v[150:153], v140 offset:1024
	ds_read_b128 v[154:157], v140 offset:2048
	ds_read_b128 v[158:161], v140 offset:3072
	v_add_u32_e32 v140, s10, v143
	ds_read_b128 v[162:165], v140
	ds_read_b128 v[166:169], v140 offset:1024
	ds_read_b128 v[170:173], v140 offset:2048
	ds_read_b128 v[174:177], v140 offset:3072
	s_add_u32 s55, s80, 0xfffc0080
	s_addc_u32 s82, s81, -1
	s_cmp_eq_u32 s94, 12
	s_cselect_b32 s85, s9, s82
	s_cselect_b32 s84, s92, s55
	s_cselect_b32 s83, s12, s93
	s_cselect_b32 s82, s13, s75
	v_lshl_add_u64 v[140:141], s[80:81], 0, v[136:137]
	s_add_i32 m0, s60, 0xc000
	ds_read_b128 v[178:181], v145
	ds_read_b128 v[182:185], v145 offset:1024
	ds_read_b128 v[186:189], v145 offset:2048
	ds_read_b128 v[192:195], v145 offset:3072
	ds_read_b128 v[196:199], v145 offset:4096
	ds_read_b128 v[200:203], v145 offset:5120
	ds_read_b128 v[204:207], v145 offset:6144
	ds_read_b128 v[208:211], v145 offset:7168
	global_load_lds_dwordx4 v[140:141], off
	v_lshl_add_u64 v[140:141], s[80:81], 0, v[138:139]
	s_add_i32 m0, s60, 0xe000
	s_nop 0
	global_load_lds_dwordx4 v[140:141], off
	s_waitcnt vmcnt(8)
	s_waitcnt lgkmcnt(0)
	s_barrier
	s_waitcnt lgkmcnt(0)
	v_mfma_f32_16x16x32_bf16 v[126:129], v[146:149], v[178:181], v[126:129]
	v_mfma_f32_16x16x32_bf16 v[122:125], v[154:157], v[178:181], v[122:125]
	v_mfma_f32_16x16x32_bf16 v[110:113], v[146:149], v[186:189], v[110:113]
	v_mfma_f32_16x16x32_bf16 v[106:109], v[154:157], v[186:189], v[106:109]
	v_mfma_f32_16x16x32_bf16 v[94:97], v[146:149], v[196:199], v[94:97]
	v_mfma_f32_16x16x32_bf16 v[90:93], v[154:157], v[196:199], v[90:93]
	v_mfma_f32_16x16x32_bf16 v[78:81], v[146:149], v[204:207], v[78:81]
	v_mfma_f32_16x16x32_bf16 v[74:77], v[154:157], v[204:207], v[74:77]
	v_mfma_f32_16x16x32_bf16 v[126:129], v[150:153], v[182:185], v[126:129]
	v_mfma_f32_16x16x32_bf16 v[122:125], v[158:161], v[182:185], v[122:125]
	v_mfma_f32_16x16x32_bf16 v[110:113], v[150:153], v[192:195], v[110:113]
	v_mfma_f32_16x16x32_bf16 v[106:109], v[158:161], v[192:195], v[106:109]
	v_mfma_f32_16x16x32_bf16 v[94:97], v[150:153], v[200:203], v[94:97]
	v_mfma_f32_16x16x32_bf16 v[90:93], v[158:161], v[200:203], v[90:93]
	v_mfma_f32_16x16x32_bf16 v[78:81], v[150:153], v[208:211], v[78:81]
	v_mfma_f32_16x16x32_bf16 v[74:77], v[158:161], v[208:211], v[74:77]
	v_mfma_f32_16x16x32_bf16 v[118:121], v[162:165], v[178:181], v[118:121]
	v_mfma_f32_16x16x32_bf16 v[114:117], v[170:173], v[178:181], v[114:117]
	v_mfma_f32_16x16x32_bf16 v[102:105], v[162:165], v[186:189], v[102:105]
	v_mfma_f32_16x16x32_bf16 v[98:101], v[170:173], v[186:189], v[98:101]
	v_mfma_f32_16x16x32_bf16 v[86:89], v[162:165], v[196:199], v[86:89]
	v_mfma_f32_16x16x32_bf16 v[82:85], v[170:173], v[196:199], v[82:85]
	v_mfma_f32_16x16x32_bf16 v[70:73], v[162:165], v[204:207], v[70:73]
	v_mfma_f32_16x16x32_bf16 v[66:69], v[170:173], v[204:207], v[66:69]
	v_mfma_f32_16x16x32_bf16 v[118:121], v[166:169], v[182:185], v[118:121]
	v_mfma_f32_16x16x32_bf16 v[114:117], v[174:177], v[182:185], v[114:117]
	v_mfma_f32_16x16x32_bf16 v[102:105], v[166:169], v[192:195], v[102:105]
	v_mfma_f32_16x16x32_bf16 v[98:101], v[174:177], v[192:195], v[98:101]
	v_mfma_f32_16x16x32_bf16 v[86:89], v[166:169], v[200:203], v[86:89]
	v_mfma_f32_16x16x32_bf16 v[82:85], v[174:177], v[200:203], v[82:85]
	v_mfma_f32_16x16x32_bf16 v[70:73], v[166:169], v[208:211], v[70:73]
	v_mfma_f32_16x16x32_bf16 v[66:69], v[174:177], v[208:211], v[66:69]
	s_barrier
	s_add_i32 s55, s63, s59
	v_lshl_add_u64 v[140:141], s[82:83], 0, v[0:1]
	s_mov_b32 m0, s55
	ds_read_b128 v[178:181], v145 offset:16384
	ds_read_b128 v[182:185], v145 offset:17408
	ds_read_b128 v[186:189], v145 offset:18432
	ds_read_b128 v[192:195], v145 offset:19456
	ds_read_b128 v[196:199], v145 offset:20480
	ds_read_b128 v[200:203], v145 offset:21504
	ds_read_b128 v[204:207], v145 offset:22528
	ds_read_b128 v[208:211], v145 offset:23552
	global_load_lds_dwordx4 v[140:141], off
	s_add_i32 m0, s55, 0x2000
	s_add_u32 s96, s82, 0x40000
	v_lshl_add_u64 v[212:213], s[82:83], 0, v[134:135]
	s_addc_u32 s97, s83, 0
	s_add_i32 s55, s10, s59
	global_load_lds_dwordx4 v[212:213], off
	v_lshl_add_u64 v[214:215], s[96:97], 0, v[0:1]
	s_mov_b32 m0, s55
	v_lshl_add_u64 v[216:217], s[84:85], 0, v[132:133]
	global_load_lds_dwordx4 v[214:215], off
	v_lshl_add_u64 v[214:215], s[96:97], 0, v[134:135]
	s_add_i32 m0, s55, 0x2000
	s_nop 0
	global_load_lds_dwordx4 v[214:215], off
	v_lshl_add_u64 v[214:215], s[84:85], 0, v[130:131]
	s_mov_b32 m0, s60
	s_nop 0
	global_load_lds_dwordx4 v[214:215], off
	s_mov_b32 m0, s61
	s_nop 0
	global_load_lds_dwordx4 v[216:217], off
	s_waitcnt vmcnt(8)
	s_waitcnt lgkmcnt(0)
	s_barrier
	s_waitcnt lgkmcnt(0)
	v_mfma_f32_16x16x32_bf16 v[62:65], v[146:149], v[178:181], v[62:65]
	v_mfma_f32_16x16x32_bf16 v[58:61], v[154:157], v[178:181], v[58:61]
	v_mfma_f32_16x16x32_bf16 v[46:49], v[146:149], v[186:189], v[46:49]
	v_mfma_f32_16x16x32_bf16 v[42:45], v[154:157], v[186:189], v[42:45]
	v_mfma_f32_16x16x32_bf16 v[30:33], v[146:149], v[196:199], v[30:33]
	v_mfma_f32_16x16x32_bf16 v[26:29], v[154:157], v[196:199], v[26:29]
	v_mfma_f32_16x16x32_bf16 v[14:17], v[146:149], v[204:207], v[14:17]
	v_mfma_f32_16x16x32_bf16 v[10:13], v[154:157], v[204:207], v[10:13]
	v_mfma_f32_16x16x32_bf16 v[62:65], v[150:153], v[182:185], v[62:65]
	v_mfma_f32_16x16x32_bf16 v[58:61], v[158:161], v[182:185], v[58:61]
	v_mfma_f32_16x16x32_bf16 v[46:49], v[150:153], v[192:195], v[46:49]
	v_mfma_f32_16x16x32_bf16 v[42:45], v[158:161], v[192:195], v[42:45]
	v_mfma_f32_16x16x32_bf16 v[30:33], v[150:153], v[200:203], v[30:33]
	v_mfma_f32_16x16x32_bf16 v[26:29], v[158:161], v[200:203], v[26:29]
	v_mfma_f32_16x16x32_bf16 v[14:17], v[150:153], v[208:211], v[14:17]
	v_mfma_f32_16x16x32_bf16 v[10:13], v[158:161], v[208:211], v[10:13]
	v_mfma_f32_16x16x32_bf16 v[54:57], v[162:165], v[178:181], v[54:57]
	v_mfma_f32_16x16x32_bf16 v[50:53], v[170:173], v[178:181], v[50:53]
	v_mfma_f32_16x16x32_bf16 v[38:41], v[162:165], v[186:189], v[38:41]
	v_mfma_f32_16x16x32_bf16 v[34:37], v[170:173], v[186:189], v[34:37]
	v_mfma_f32_16x16x32_bf16 v[22:25], v[162:165], v[196:199], v[22:25]
	v_mfma_f32_16x16x32_bf16 v[18:21], v[170:173], v[196:199], v[18:21]
	v_mfma_f32_16x16x32_bf16 v[6:9], v[162:165], v[204:207], v[6:9]
	v_mfma_f32_16x16x32_bf16 v[2:5], v[170:173], v[204:207], v[2:5]
	v_mfma_f32_16x16x32_bf16 v[54:57], v[166:169], v[182:185], v[54:57]
	v_mfma_f32_16x16x32_bf16 v[50:53], v[174:177], v[182:185], v[50:53]
	v_mfma_f32_16x16x32_bf16 v[38:41], v[166:169], v[192:195], v[38:41]
	v_mfma_f32_16x16x32_bf16 v[34:37], v[174:177], v[192:195], v[34:37]
	v_mfma_f32_16x16x32_bf16 v[22:25], v[166:169], v[200:203], v[22:25]
	v_mfma_f32_16x16x32_bf16 v[18:21], v[174:177], v[200:203], v[18:21]
	v_mfma_f32_16x16x32_bf16 v[6:9], v[166:169], v[208:211], v[6:9]
	v_mfma_f32_16x16x32_bf16 v[2:5], v[174:177], v[208:211], v[2:5]
	s_barrier
	v_add_u32_e32 v158, s11, v143
	v_add_u32_e32 v174, s67, v143
	ds_read_b128 v[146:149], v158
	ds_read_b128 v[150:153], v158 offset:1024
	ds_read_b128 v[154:157], v158 offset:2048
	ds_read_b128 v[158:161], v158 offset:3072
	ds_read_b128 v[162:165], v174
	ds_read_b128 v[166:169], v174 offset:1024
	ds_read_b128 v[170:173], v174 offset:2048
	ds_read_b128 v[174:177], v174 offset:3072
	s_add_u32 s84, s84, 0x40000
	s_addc_u32 s85, s85, 0
	s_mov_b32 m0, s68
	v_lshl_add_u64 v[218:219], s[84:85], 0, v[130:131]
	ds_read_b128 v[178:181], v145 offset:32768
	ds_read_b128 v[182:185], v145 offset:33792
	ds_read_b128 v[186:189], v145 offset:34816
	ds_read_b128 v[192:195], v145 offset:35840
	ds_read_b128 v[196:199], v145 offset:36864
	ds_read_b128 v[200:203], v145 offset:37888
	ds_read_b128 v[204:207], v145 offset:38912
	ds_read_b128 v[208:211], v145 offset:39936
	global_load_lds_dwordx4 v[218:219], off
	v_lshl_add_u64 v[218:219], s[84:85], 0, v[132:133]
	s_mov_b32 m0, s69
	s_nop 0
	global_load_lds_dwordx4 v[218:219], off
	s_waitcnt vmcnt(8)
	s_waitcnt lgkmcnt(0)
	s_barrier
	s_waitcnt lgkmcnt(0)
	v_mfma_f32_16x16x32_bf16 v[126:129], v[146:149], v[178:181], v[126:129]
	v_mfma_f32_16x16x32_bf16 v[122:125], v[154:157], v[178:181], v[122:125]
	v_mfma_f32_16x16x32_bf16 v[110:113], v[146:149], v[186:189], v[110:113]
	v_mfma_f32_16x16x32_bf16 v[106:109], v[154:157], v[186:189], v[106:109]
	v_mfma_f32_16x16x32_bf16 v[94:97], v[146:149], v[196:199], v[94:97]
	v_mfma_f32_16x16x32_bf16 v[90:93], v[154:157], v[196:199], v[90:93]
	v_mfma_f32_16x16x32_bf16 v[78:81], v[146:149], v[204:207], v[78:81]
	v_mfma_f32_16x16x32_bf16 v[74:77], v[154:157], v[204:207], v[74:77]
	v_mfma_f32_16x16x32_bf16 v[126:129], v[150:153], v[182:185], v[126:129]
	v_mfma_f32_16x16x32_bf16 v[122:125], v[158:161], v[182:185], v[122:125]
	v_mfma_f32_16x16x32_bf16 v[110:113], v[150:153], v[192:195], v[110:113]
	v_mfma_f32_16x16x32_bf16 v[106:109], v[158:161], v[192:195], v[106:109]
	v_mfma_f32_16x16x32_bf16 v[94:97], v[150:153], v[200:203], v[94:97]
	v_mfma_f32_16x16x32_bf16 v[90:93], v[158:161], v[200:203], v[90:93]
	v_mfma_f32_16x16x32_bf16 v[78:81], v[150:153], v[208:211], v[78:81]
	v_mfma_f32_16x16x32_bf16 v[74:77], v[158:161], v[208:211], v[74:77]
	v_mfma_f32_16x16x32_bf16 v[118:121], v[162:165], v[178:181], v[118:121]
	v_mfma_f32_16x16x32_bf16 v[114:117], v[170:173], v[178:181], v[114:117]
	v_mfma_f32_16x16x32_bf16 v[102:105], v[162:165], v[186:189], v[102:105]
	v_mfma_f32_16x16x32_bf16 v[98:101], v[170:173], v[186:189], v[98:101]
	v_mfma_f32_16x16x32_bf16 v[86:89], v[162:165], v[196:199], v[86:89]
	v_mfma_f32_16x16x32_bf16 v[82:85], v[170:173], v[196:199], v[82:85]
	v_mfma_f32_16x16x32_bf16 v[70:73], v[162:165], v[204:207], v[70:73]
	v_mfma_f32_16x16x32_bf16 v[66:69], v[170:173], v[204:207], v[66:69]
	v_mfma_f32_16x16x32_bf16 v[118:121], v[166:169], v[182:185], v[118:121]
	v_mfma_f32_16x16x32_bf16 v[114:117], v[174:177], v[182:185], v[114:117]
	v_mfma_f32_16x16x32_bf16 v[102:105], v[166:169], v[192:195], v[102:105]
	v_mfma_f32_16x16x32_bf16 v[98:101], v[174:177], v[192:195], v[98:101]
	v_mfma_f32_16x16x32_bf16 v[86:89], v[166:169], v[200:203], v[86:89]
	v_mfma_f32_16x16x32_bf16 v[82:85], v[174:177], v[200:203], v[82:85]
	v_mfma_f32_16x16x32_bf16 v[70:73], v[166:169], v[208:211], v[70:73]
	v_mfma_f32_16x16x32_bf16 v[66:69], v[174:177], v[208:211], v[66:69]
	s_barrier
	s_add_i32 s55, s11, s59
	v_lshl_add_u64 v[140:141], v[140:141], 0, s[50:51]
	s_mov_b32 m0, s55
	ds_read_b128 v[178:181], v145 offset:49152
	ds_read_b128 v[182:185], v145 offset:50176
	ds_read_b128 v[186:189], v145 offset:51200
	ds_read_b128 v[192:195], v145 offset:52224
	ds_read_b128 v[196:199], v145 offset:53248
	ds_read_b128 v[200:203], v145 offset:54272
	ds_read_b128 v[204:207], v145 offset:55296
	ds_read_b128 v[208:211], v145 offset:56320
	global_load_lds_dwordx4 v[140:141], off
	s_add_i32 m0, s55, 0x2000
	s_add_u32 s82, s82, 0x40080
	v_lshl_add_u64 v[140:141], v[212:213], 0, s[50:51]
	s_addc_u32 s83, s83, 0
	s_add_i32 s55, s67, s59
	global_load_lds_dwordx4 v[140:141], off
	v_lshl_add_u64 v[140:141], s[82:83], 0, v[0:1]
	s_mov_b32 m0, s55
	s_nop 0
	global_load_lds_dwordx4 v[140:141], off
	v_lshl_add_u64 v[140:141], s[82:83], 0, v[134:135]
	s_add_i32 m0, s55, 0x2000
	s_nop 0
	global_load_lds_dwordx4 v[140:141], off
	v_lshl_add_u64 v[140:141], v[214:215], 0, s[50:51]
	s_mov_b32 m0, s86
	s_nop 0
	global_load_lds_dwordx4 v[140:141], off
	v_lshl_add_u64 v[140:141], v[216:217], 0, s[50:51]
	s_mov_b32 m0, s87
	s_nop 0
	global_load_lds_dwordx4 v[140:141], off
	s_waitcnt vmcnt(8)
	s_waitcnt lgkmcnt(0)
	s_barrier
	s_waitcnt lgkmcnt(0)
	v_mfma_f32_16x16x32_bf16 v[62:65], v[146:149], v[178:181], v[62:65]
	v_mfma_f32_16x16x32_bf16 v[58:61], v[154:157], v[178:181], v[58:61]
	v_mfma_f32_16x16x32_bf16 v[46:49], v[146:149], v[186:189], v[46:49]
	v_mfma_f32_16x16x32_bf16 v[42:45], v[154:157], v[186:189], v[42:45]
	v_mfma_f32_16x16x32_bf16 v[30:33], v[146:149], v[196:199], v[30:33]
	v_mfma_f32_16x16x32_bf16 v[26:29], v[154:157], v[196:199], v[26:29]
	v_mfma_f32_16x16x32_bf16 v[14:17], v[146:149], v[204:207], v[14:17]
	v_mfma_f32_16x16x32_bf16 v[10:13], v[154:157], v[204:207], v[10:13]
	v_mfma_f32_16x16x32_bf16 v[62:65], v[150:153], v[182:185], v[62:65]
	v_mfma_f32_16x16x32_bf16 v[58:61], v[158:161], v[182:185], v[58:61]
	v_mfma_f32_16x16x32_bf16 v[46:49], v[150:153], v[192:195], v[46:49]
	v_mfma_f32_16x16x32_bf16 v[42:45], v[158:161], v[192:195], v[42:45]
	v_mfma_f32_16x16x32_bf16 v[30:33], v[150:153], v[200:203], v[30:33]
	v_mfma_f32_16x16x32_bf16 v[26:29], v[158:161], v[200:203], v[26:29]
	v_mfma_f32_16x16x32_bf16 v[14:17], v[150:153], v[208:211], v[14:17]
	v_mfma_f32_16x16x32_bf16 v[10:13], v[158:161], v[208:211], v[10:13]
	v_mfma_f32_16x16x32_bf16 v[54:57], v[162:165], v[178:181], v[54:57]
	v_mfma_f32_16x16x32_bf16 v[50:53], v[170:173], v[178:181], v[50:53]
	v_mfma_f32_16x16x32_bf16 v[38:41], v[162:165], v[186:189], v[38:41]
	v_mfma_f32_16x16x32_bf16 v[34:37], v[170:173], v[186:189], v[34:37]
	v_mfma_f32_16x16x32_bf16 v[22:25], v[162:165], v[196:199], v[22:25]
	v_mfma_f32_16x16x32_bf16 v[18:21], v[170:173], v[196:199], v[18:21]
	v_mfma_f32_16x16x32_bf16 v[6:9], v[162:165], v[204:207], v[6:9]
	v_mfma_f32_16x16x32_bf16 v[2:5], v[170:173], v[204:207], v[2:5]
	v_mfma_f32_16x16x32_bf16 v[54:57], v[166:169], v[182:185], v[54:57]
	v_mfma_f32_16x16x32_bf16 v[50:53], v[174:177], v[182:185], v[50:53]
	v_mfma_f32_16x16x32_bf16 v[38:41], v[166:169], v[192:195], v[38:41]
	v_mfma_f32_16x16x32_bf16 v[34:37], v[174:177], v[192:195], v[34:37]
	v_mfma_f32_16x16x32_bf16 v[22:25], v[166:169], v[200:203], v[22:25]
	v_mfma_f32_16x16x32_bf16 v[18:21], v[174:177], v[200:203], v[18:21]
	v_mfma_f32_16x16x32_bf16 v[6:9], v[166:169], v[208:211], v[6:9]
	v_mfma_f32_16x16x32_bf16 v[2:5], v[174:177], v[208:211], v[2:5]
	s_barrier
	s_add_i32 s94, s94, 2
	s_add_u32 s80, s80, 0x100
	s_addc_u32 s81, s81, 0
	s_add_u32 s75, s75, 0x100
	s_addc_u32 s93, s93, 0
	s_cmp_gt_u32 s94, 13
	s_cbranch_scc0 .LBB0_883
	s_and_b64 vcc, exec, s[6:7]
	s_cbranch_vccz .LBB0_886
	s_barrier

.LBB0_889:
	s_setprio 0
	s_mov_b64 s[2:3], s[0:1]
	s_waitcnt vmcnt(0)
	s_barrier
	s_load_dwordx2 s[4:5], s[2:3], 0x80
	s_mov_b64 s[6:7], 0
	s_and_b64 vcc, exec, s[84:85]
	s_getreg_b32 s8, hwreg(HW_REG_XCC_ID, 0, 4)
	s_cbranch_vccnz .LBB0_891
	v_mov_b32_e32 v0, v220
	s_nop 0
	v_cmp_eq_u32_e32 vcc, 0, v0
	s_and_b64 s[6:7], vcc, exec
